# SwiGLU epilogue + per-tile accumulator clear by 32x32x16 MFMA on zero operands instead of v_mov runs
# speedup vs baseline: 1.0011x; 1.0011x over previous
; template <class Epi>
; __device__ __forceinline__ void gemm_phase(LAS unsigned char* lds, const Gemm g, const StaticOrder& S, const Epi& E, int wave_s) {
;     ...
;         const bool has_next = S.next(ui + 1, nxt);
;         const char* nA = has_next ? (const char*)g.A + (size_t)nxt.pm * tstepA : cA; const char* nB = has_next ? (const char*)g.Bt + (size_t)nxt.pn * tstepB : cB;
;         for (int t = 0; t < nt; t += 2) {
;             const bool last = (t == nt - 2);
;             const char* a1 = cA + (size_t)(t + 1) * kstep;
;             const char* a2 = last ? nA : cA + (size_t)(t + 2) * kstep; const char* b2 = last ? nB : cB + (size_t)(t + 2) * kstep;
;     ...
; #pragma unroll
;         for (int a = 0; a < 2; ++a)
; #pragma unroll
;             for (int b = 0; b < 2; ++b)
; #pragma unroll
;                 for (int m = 0; m < 4; ++m)
; #pragma unroll
;                     for (int n = 0; n < 2; ++n) acc[a][b][m][n] = (f32x4){0.f, 0.f, 0.f, 0.f};
;         cur = nxt; cA = nA; cB = nB; ++ui;
.LBB0_240:
	s_ashr_i32 s25, s24, 31
	s_lshl_b64 s[26:27], s[24:25], 19
	s_add_u32 s26, s0, s26
	s_addc_u32 s27, s1, s27
	s_and_b64 s[30:31], s[6:7], exec
	s_cselect_b32 s9, s27, s35
	s_cselect_b32 s25, s26, s34
	s_ashr_i32 s23, s22, 31
	s_lshl_b64 s[30:31], s[22:23], 19
	s_add_u32 s30, s29, s30
	s_addc_u32 s31, s33, s31
	s_and_b64 s[38:39], s[6:7], exec
	s_cselect_b32 s23, s31, s37
	s_cselect_b32 s57, s30, s36
	s_add_u32 s34, s34, 0x40080
	s_addc_u32 s35, s35, 0
	s_add_u32 s58, s36, 0x100
	v_mov_b32_e32 v0, 0
	s_addc_u32 s59, s37, 0
	s_mov_b32 s60, -2
	v_mov_b32_e32 v1, v0
	v_mov_b32_e32 v2, v0
	v_mov_b32_e32 v3, v0
	v_mov_b32_e32 v4, v0
	v_mov_b32_e32 v5, v0
	v_mov_b32_e32 v6, v0
	v_mov_b32_e32 v7, v0
	v_mov_b32_e32 v8, v0
	v_mov_b32_e32 v9, v0
	v_mov_b32_e32 v10, v0
	v_mov_b32_e32 v11, v0
	v_mov_b32_e32 v12, v0
	v_mov_b32_e32 v13, v0
	v_mov_b32_e32 v14, v0
	v_mov_b32_e32 v15, v0
	s_nop 1
	v_mfma_f32_32x32x16_bf16 v[16:31], v[0:3], v[4:7], 0
	v_mfma_f32_32x32x16_bf16 v[32:47], v[0:3], v[4:7], 0
	v_mfma_f32_32x32x16_bf16 v[48:63], v[0:3], v[4:7], 0
	v_mfma_f32_32x32x16_bf16 v[64:79], v[0:3], v[4:7], 0
	v_mfma_f32_32x32x16_bf16 v[80:95], v[0:3], v[4:7], 0
	v_mfma_f32_32x32x16_bf16 v[96:111], v[0:3], v[4:7], 0
	v_mfma_f32_32x32x16_bf16 v[112:127], v[0:3], v[4:7], 0

; template <class Epi>
; __device__ __forceinline__ void gemm_phase(LAS unsigned char* lds, const Gemm g, const StaticOrder& S, const Epi& E, int wave_s) {
;     ...
; #pragma unroll
;         for (int a = 0; a < 2; ++a)
; #pragma unroll
;             for (int b = 0; b < 2; ++b)
; #pragma unroll
;                 for (int m = 0; m < 4; ++m)
; #pragma unroll
;                     for (int n = 0; n < 2; ++n) acc[a][b][m][n] = (f32x4){0.f, 0.f, 0.f, 0.f};
.LBB0_263:
	s_ashr_i32 s53, s52, 31
	s_lshl_b64 s[54:55], s[52:53], 19
	s_add_u32 s54, s0, s54
	s_addc_u32 s55, s1, s55
	s_and_b64 s[56:57], s[48:49], exec
	s_cselect_b32 s53, s55, s9
	s_cselect_b32 s84, s54, s8
	s_ashr_i32 s51, s50, 31
	s_lshl_b64 s[56:57], s[50:51], 19
	s_add_u32 s56, s70, s56
	s_addc_u32 s57, s71, s57
	s_and_b64 s[60:61], s[48:49], exec
	s_cselect_b32 s51, s57, s59
	s_cselect_b32 s85, s56, s58
	s_add_u32 s8, s8, 0x40080
	s_addc_u32 s9, s9, 0
	s_add_u32 s86, s58, 0x100
	v_mov_b32_e32 v0, 0
	s_addc_u32 s87, s59, 0
	s_mov_b32 s88, -2
	v_mov_b32_e32 v1, v0
	v_mov_b32_e32 v2, v0
	v_mov_b32_e32 v3, v0
	v_mov_b32_e32 v4, v0
	v_mov_b32_e32 v5, v0
	v_mov_b32_e32 v6, v0
	v_mov_b32_e32 v7, v0
	v_mov_b32_e32 v8, v0
	v_mov_b32_e32 v9, v0
	v_mov_b32_e32 v10, v0
	v_mov_b32_e32 v11, v0
	v_mov_b32_e32 v12, v0
	v_mov_b32_e32 v13, v0
	v_mov_b32_e32 v14, v0
	v_mov_b32_e32 v15, v0
	s_nop 1
	v_mfma_f32_32x32x16_bf16 v[16:31], v[0:3], v[4:7], 0
	v_mfma_f32_32x32x16_bf16 v[32:47], v[0:3], v[4:7], 0
	v_mfma_f32_32x32x16_bf16 v[48:63], v[0:3], v[4:7], 0
	v_mfma_f32_32x32x16_bf16 v[64:79], v[0:3], v[4:7], 0
	v_mfma_f32_32x32x16_bf16 v[80:95], v[0:3], v[4:7], 0
	v_mfma_f32_32x32x16_bf16 v[96:111], v[0:3], v[4:7], 0
	v_mfma_f32_32x32x16_bf16 v[112:127], v[0:3], v[4:7], 0

; template <class Epi>
; __device__ __forceinline__ void gemm_phase(LAS unsigned char* lds, const Gemm g, const StaticOrder& S, const Epi& E, int wave_s) {
;     ...
; #pragma unroll
;         for (int a = 0; a < 2; ++a)
; #pragma unroll
;             for (int b = 0; b < 2; ++b)
; #pragma unroll
;                 for (int m = 0; m < 4; ++m)
; #pragma unroll
;                     for (int n = 0; n < 2; ++n) acc[a][b][m][n] = (f32x4){0.f, 0.f, 0.f, 0.f};
.LBB0_283:
	s_ashr_i32 s53, s52, 31
	s_lshl_b64 s[54:55], s[52:53], 19
	s_add_u32 s54, s60, s54
	s_addc_u32 s55, s61, s55
	s_and_b64 s[56:57], s[48:49], exec
	s_cselect_b32 s53, s55, s7
	s_cselect_b32 s77, s54, s6
	s_ashr_i32 s51, s50, 31
	s_lshl_b64 s[56:57], s[50:51], 19
	s_add_u32 s56, s0, s56
	s_addc_u32 s57, s1, s57
	s_and_b64 s[58:59], s[48:49], exec
	s_cselect_b32 s51, s57, s9
	s_cselect_b32 s78, s56, s8
	s_add_u32 s6, s6, 0x40080
	s_addc_u32 s7, s7, 0
	s_add_u32 s79, s8, 0x100
	v_mov_b32_e32 v0, 0
	s_addc_u32 s82, s9, 0
	s_mov_b32 s83, -2
	v_mov_b32_e32 v1, v0
	v_mov_b32_e32 v2, v0
	v_mov_b32_e32 v3, v0
	v_mov_b32_e32 v4, v0
	v_mov_b32_e32 v5, v0
	v_mov_b32_e32 v6, v0
	v_mov_b32_e32 v7, v0
	v_mov_b32_e32 v8, v0
	v_mov_b32_e32 v9, v0
	v_mov_b32_e32 v10, v0
	v_mov_b32_e32 v11, v0
	v_mov_b32_e32 v12, v0
	v_mov_b32_e32 v13, v0
	v_mov_b32_e32 v14, v0
	v_mov_b32_e32 v15, v0
	s_nop 1
	v_mfma_f32_32x32x16_bf16 v[16:31], v[0:3], v[4:7], 0
	v_mfma_f32_32x32x16_bf16 v[32:47], v[0:3], v[4:7], 0
	v_mfma_f32_32x32x16_bf16 v[48:63], v[0:3], v[4:7], 0
	v_mfma_f32_32x32x16_bf16 v[64:79], v[0:3], v[4:7], 0
	v_mfma_f32_32x32x16_bf16 v[80:95], v[0:3], v[4:7], 0
	v_mfma_f32_32x32x16_bf16 v[96:111], v[0:3], v[4:7], 0
	v_mfma_f32_32x32x16_bf16 v[112:127], v[0:3], v[4:7], 0

; template <class Epi>
; __device__ __forceinline__ void gemm_phase(LAS unsigned char* lds, const Gemm g, const StaticOrder& S, const Epi& E, int wave_s) {
;     ...
; #pragma unroll
;         for (int a = 0; a < 2; ++a)
; #pragma unroll
;             for (int b = 0; b < 2; ++b)
; #pragma unroll
;                 for (int m = 0; m < 4; ++m)
; #pragma unroll
;                     for (int n = 0; n < 2; ++n) acc[a][b][m][n] = (f32x4){0.f, 0.f, 0.f, 0.f};
.LBB0_369:
	s_add_u32 s59, s40, 0x100
	v_mov_b32_e32 v0, 0
	s_addc_u32 s60, s41, 0
	s_mov_b32 s61, -2
	s_waitcnt lgkmcnt(0)
	v_mov_b32_e32 v1, v0
	v_mov_b32_e32 v2, v0
	v_mov_b32_e32 v3, v0
	v_mov_b32_e32 v4, v0
	v_mov_b32_e32 v5, v0
	v_mov_b32_e32 v6, v0
	v_mov_b32_e32 v7, v0
	v_mov_b32_e32 v8, v0
	v_mov_b32_e32 v9, v0
	v_mov_b32_e32 v10, v0
	v_mov_b32_e32 v11, v0
	v_mov_b32_e32 v12, v0
	v_mov_b32_e32 v13, v0
	v_mov_b32_e32 v14, v0
	v_mov_b32_e32 v15, v0
	s_nop 1
	v_mfma_f32_32x32x16_bf16 v[16:31], v[0:3], v[4:7], 0
	v_mfma_f32_32x32x16_bf16 v[32:47], v[0:3], v[4:7], 0
	v_mfma_f32_32x32x16_bf16 v[48:63], v[0:3], v[4:7], 0
	v_mfma_f32_32x32x16_bf16 v[64:79], v[0:3], v[4:7], 0
	v_mfma_f32_32x32x16_bf16 v[80:95], v[0:3], v[4:7], 0
	v_mfma_f32_32x32x16_bf16 v[96:111], v[0:3], v[4:7], 0
	v_mfma_f32_32x32x16_bf16 v[112:127], v[0:3], v[4:7], 0

; template <class Epi>
; __device__ __forceinline__ void gemm_phase(LAS unsigned char* lds, const Gemm g, const StaticOrder& S, const Epi& E, int wave_s) {
;     ...
; #pragma unroll
;         for (int a = 0; a < 2; ++a)
; #pragma unroll
;             for (int b = 0; b < 2; ++b)
; #pragma unroll
;                 for (int m = 0; m < 4; ++m)
; #pragma unroll
;                     for (int n = 0; n < 2; ++n) acc[a][b][m][n] = (f32x4){0.f, 0.f, 0.f, 0.f};
.LBB0_471:
	s_ashr_i32 s31, s30, 31
	s_lshl_b64 s[0:1], s[30:31], 19
	s_add_u32 s34, s3, s0
	s_addc_u32 s35, s4, s1
	s_and_b64 s[0:1], s[6:7], exec
	s_cselect_b32 s0, s35, s11
	s_cselect_b32 s1, s34, s10
	s_ashr_i32 s29, s28, 31
	s_lshl_b64 s[36:37], s[28:29], 19
	s_add_u32 s36, s45, s36
	s_addc_u32 s37, s46, s37
	s_and_b64 s[40:41], s[6:7], exec
	s_cselect_b32 s2, s37, s39
	s_cselect_b32 s9, s36, s38
	s_add_u32 s10, s10, 0x40080
	s_addc_u32 s11, s11, 0
	s_add_u32 s29, s38, 0x100
	v_mov_b32_e32 v0, 0
	s_addc_u32 s31, s39, 0
	s_mov_b32 s33, -2
	v_mov_b32_e32 v1, v0
	v_mov_b32_e32 v2, v0
	v_mov_b32_e32 v3, v0
	v_mov_b32_e32 v4, v0
	v_mov_b32_e32 v5, v0
	v_mov_b32_e32 v6, v0
	v_mov_b32_e32 v7, v0
	v_mov_b32_e32 v8, v0
	v_mov_b32_e32 v9, v0
	v_mov_b32_e32 v10, v0
	v_mov_b32_e32 v11, v0
	v_mov_b32_e32 v12, v0
	v_mov_b32_e32 v13, v0
	v_mov_b32_e32 v14, v0
	v_mov_b32_e32 v15, v0
	s_nop 1
	v_mfma_f32_32x32x16_bf16 v[16:31], v[0:3], v[4:7], 0
	v_mfma_f32_32x32x16_bf16 v[32:47], v[0:3], v[4:7], 0
	v_mfma_f32_32x32x16_bf16 v[48:63], v[0:3], v[4:7], 0
	v_mfma_f32_32x32x16_bf16 v[64:79], v[0:3], v[4:7], 0
	v_mfma_f32_32x32x16_bf16 v[80:95], v[0:3], v[4:7], 0
	v_mfma_f32_32x32x16_bf16 v[96:111], v[0:3], v[4:7], 0
	v_mfma_f32_32x32x16_bf16 v[112:127], v[0:3], v[4:7], 0

; template <class Epi>
; __device__ __forceinline__ void gemm_phase(LAS unsigned char* lds, const Gemm g, const StaticOrder& S, const Epi& E, int wave_s) {
;     ...
; #pragma unroll
;         for (int a = 0; a < 2; ++a)
; #pragma unroll
;             for (int b = 0; b < 2; ++b)
; #pragma unroll
;                 for (int m = 0; m < 4; ++m)
; #pragma unroll
;                     for (int n = 0; n < 2; ++n) acc[a][b][m][n] = (f32x4){0.f, 0.f, 0.f, 0.f};
.LBB0_499:
	s_ashr_i32 s37, s36, 31
	s_lshl_b64 s[38:39], s[36:37], 19
	s_add_u32 s38, s1, s38
	s_addc_u32 s39, s33, s39
	s_and_b64 s[40:41], s[6:7], exec
	s_cselect_b32 s37, s39, s9
	s_cselect_b32 s61, s38, s8
	s_ashr_i32 s35, s34, 31
	s_lshl_b64 s[40:41], s[34:35], 19
	s_add_u32 s40, s3, s40
	s_addc_u32 s41, s4, s41
	s_and_b64 s[44:45], s[6:7], exec
	s_cselect_b32 s35, s41, s11
	s_cselect_b32 s62, s40, s10
	s_add_u32 s8, s8, 0x40080
	s_addc_u32 s9, s9, 0
	s_add_u32 s63, s10, 0x100
	v_mov_b32_e32 v0, 0
	s_addc_u32 s64, s11, 0
	s_mov_b32 s65, -2
	v_mov_b32_e32 v1, v0
	v_mov_b32_e32 v2, v0
	v_mov_b32_e32 v3, v0
	v_mov_b32_e32 v4, v0
	v_mov_b32_e32 v5, v0
	v_mov_b32_e32 v6, v0
	v_mov_b32_e32 v7, v0
	v_mov_b32_e32 v8, v0
	v_mov_b32_e32 v9, v0
	v_mov_b32_e32 v10, v0
	v_mov_b32_e32 v11, v0
	v_mov_b32_e32 v12, v0
	v_mov_b32_e32 v13, v0
	v_mov_b32_e32 v14, v0
	v_mov_b32_e32 v15, v0
	s_nop 1
	v_mfma_f32_32x32x16_bf16 v[16:31], v[0:3], v[4:7], 0
	v_mfma_f32_32x32x16_bf16 v[32:47], v[0:3], v[4:7], 0
	v_mfma_f32_32x32x16_bf16 v[48:63], v[0:3], v[4:7], 0
	v_mfma_f32_32x32x16_bf16 v[64:79], v[0:3], v[4:7], 0
	v_mfma_f32_32x32x16_bf16 v[80:95], v[0:3], v[4:7], 0
	v_mfma_f32_32x32x16_bf16 v[96:111], v[0:3], v[4:7], 0
	v_mfma_f32_32x32x16_bf16 v[112:127], v[0:3], v[4:7], 0

; template <class Epi>
; __device__ __forceinline__ void gemm_phase(LAS unsigned char* lds, const Gemm g, const StaticOrder& S, const Epi& E, int wave_s) {
;     ...
; #pragma unroll
;         for (int a = 0; a < 2; ++a)
; #pragma unroll
;             for (int b = 0; b < 2; ++b)
; #pragma unroll
;                 for (int m = 0; m < 4; ++m)
; #pragma unroll
;                     for (int n = 0; n < 2; ++n) acc[a][b][m][n] = (f32x4){0.f, 0.f, 0.f, 0.f};
.LBB0_713:
	s_ashr_i32 s27, s26, 31
	s_lshl_b64 s[28:29], s[26:27], 19
	s_add_u32 s28, s0, s28
	s_addc_u32 s29, s1, s29
	s_and_b64 s[30:31], s[8:9], exec
	s_cselect_b32 s27, s29, s37
	s_cselect_b32 s35, s28, s36
	s_ashr_i32 s25, s24, 31
	s_lshl_b64 s[30:31], s[24:25], 19
	s_add_u32 s30, s2, s30
	s_addc_u32 s31, s3, s31
	s_and_b64 s[40:41], s[8:9], exec
	s_cselect_b32 s25, s31, s39
	s_cselect_b32 s53, s30, s38
	s_add_u32 s36, s36, 0x40080
	s_addc_u32 s37, s37, 0
	s_add_u32 s54, s38, 0x100
	v_mov_b32_e32 v0, 0
	s_addc_u32 s55, s39, 0
	s_mov_b32 s56, -2
	v_mov_b32_e32 v1, v0
	v_mov_b32_e32 v2, v0
	v_mov_b32_e32 v3, v0
	v_mov_b32_e32 v4, v0
	v_mov_b32_e32 v5, v0
	v_mov_b32_e32 v6, v0
	v_mov_b32_e32 v7, v0
	v_mov_b32_e32 v8, v0
	v_mov_b32_e32 v9, v0
	v_mov_b32_e32 v10, v0
	v_mov_b32_e32 v11, v0
	v_mov_b32_e32 v12, v0
	v_mov_b32_e32 v13, v0
	v_mov_b32_e32 v14, v0
	v_mov_b32_e32 v15, v0
	s_waitcnt vmcnt(0)
	v_mov_b32_e32 v112, v0
	v_mov_b32_e32 v113, v0
	v_mov_b32_e32 v114, v0
	v_mov_b32_e32 v115, v0
	v_mov_b32_e32 v116, v0
	v_mov_b32_e32 v117, v0
	v_mov_b32_e32 v118, v0
	v_mov_b32_e32 v119, v0
	v_mov_b32_e32 v144, v0
	v_mov_b32_e32 v145, v0
	v_mov_b32_e32 v146, v0
	v_mov_b32_e32 v147, v0
	v_mov_b32_e32 v148, v0
	v_mov_b32_e32 v149, v0
	v_mov_b32_e32 v150, v0
	v_mov_b32_e32 v151, v0
	s_nop 1
	v_mfma_f32_32x32x16_bf16 v[16:31], v[0:3], v[4:7], 0
	v_mfma_f32_32x32x16_bf16 v[32:47], v[0:3], v[4:7], 0
	v_mfma_f32_32x32x16_bf16 v[48:63], v[0:3], v[4:7], 0
	v_mfma_f32_32x32x16_bf16 v[64:79], v[0:3], v[4:7], 0
	v_mfma_f32_32x32x16_bf16 v[80:95], v[0:3], v[4:7], 0
	v_mfma_f32_32x32x16_bf16 v[96:111], v[0:3], v[4:7], 0

; template <class Epi>
; __device__ __forceinline__ void gemm_phase(LAS unsigned char* lds, const Gemm g, const StaticOrder& S, const Epi& E, int wave_s) {
;     ...
; #pragma unroll
;         for (int a = 0; a < 2; ++a)
; #pragma unroll
;             for (int b = 0; b < 2; ++b)
; #pragma unroll
;                 for (int m = 0; m < 4; ++m)
; #pragma unroll
;                     for (int n = 0; n < 2; ++n) acc[a][b][m][n] = (f32x4){0.f, 0.f, 0.f, 0.f};
.LBB0_810:
	s_ashr_i32 s25, s24, 31
	s_lshl_b64 s[26:27], s[24:25], 19
	s_add_u32 s26, s1, s26
	s_addc_u32 s27, s2, s27
	s_and_b64 s[28:29], s[6:7], exec
	s_cselect_b32 s25, s27, s31
	s_cselect_b32 s49, s26, s30
	s_ashr_i32 s23, s22, 31
	s_lshl_b64 s[28:29], s[22:23], 19
	s_add_u32 s28, s3, s28
	s_addc_u32 s29, s4, s29
	s_and_b64 s[36:37], s[6:7], exec
	s_cselect_b32 s23, s29, s35
	s_cselect_b32 s50, s28, s34
	s_add_u32 s30, s30, 0x40080
	s_addc_u32 s31, s31, 0
	s_add_u32 s51, s34, 0x100
	v_mov_b32_e32 v0, 0
	s_addc_u32 s52, s35, 0
	s_mov_b32 s53, -2
	v_mov_b32_e32 v1, v0
	v_mov_b32_e32 v2, v0
	v_mov_b32_e32 v3, v0
	v_mov_b32_e32 v4, v0
	v_mov_b32_e32 v5, v0
	v_mov_b32_e32 v6, v0
	v_mov_b32_e32 v7, v0
	v_mov_b32_e32 v8, v0
	v_mov_b32_e32 v9, v0
	v_mov_b32_e32 v10, v0
	v_mov_b32_e32 v11, v0
	v_mov_b32_e32 v12, v0
	v_mov_b32_e32 v13, v0
	v_mov_b32_e32 v14, v0
	v_mov_b32_e32 v15, v0
	s_nop 1
	v_mfma_f32_32x32x16_bf16 v[16:31], v[0:3], v[4:7], 0
	v_mfma_f32_32x32x16_bf16 v[32:47], v[0:3], v[4:7], 0
	v_mfma_f32_32x32x16_bf16 v[48:63], v[0:3], v[4:7], 0
	v_mfma_f32_32x32x16_bf16 v[64:79], v[0:3], v[4:7], 0
	v_mfma_f32_32x32x16_bf16 v[80:95], v[0:3], v[4:7], 0
	v_mfma_f32_32x32x16_bf16 v[96:111], v[0:3], v[4:7], 0
	v_mfma_f32_32x32x16_bf16 v[112:127], v[0:3], v[4:7], 0

; template <class Epi>
; __device__ __forceinline__ void gemm_phase(LAS unsigned char* lds, const Gemm g, const StaticOrder& S, const Epi& E, int wave_s) {
;     ...
; #pragma unroll
;         for (int a = 0; a < 2; ++a)
; #pragma unroll
;             for (int b = 0; b < 2; ++b)
; #pragma unroll
;                 for (int m = 0; m < 4; ++m)
; #pragma unroll
;                     for (int n = 0; n < 2; ++n) acc[a][b][m][n] = (f32x4){0.f, 0.f, 0.f, 0.f};
.LBB0_961:
	s_ashr_i32 s27, s26, 31
	s_lshl_b64 s[28:29], s[26:27], 18
	s_add_u32 s28, s0, s28
	s_addc_u32 s29, s1, s29
	s_and_b64 s[30:31], s[8:9], exec
	s_cselect_b32 s27, s29, s37
	s_cselect_b32 s35, s28, s36
	s_ashr_i32 s25, s24, 31
	s_lshl_b64 s[30:31], s[24:25], 18
	s_add_u32 s30, s2, s30
	s_addc_u32 s31, s3, s31
	s_and_b64 s[40:41], s[8:9], exec
	s_cselect_b32 s25, s31, s39
	s_cselect_b32 s53, s30, s38
	s_add_u32 s36, s36, 0x20080
	s_addc_u32 s37, s37, 0
	s_add_u32 s54, s38, 0x100
	v_mov_b32_e32 v0, 0
	s_addc_u32 s55, s39, 0
	s_mov_b32 s56, -2
	v_mov_b32_e32 v1, v0
	v_mov_b32_e32 v2, v0
	v_mov_b32_e32 v3, v0
	v_mov_b32_e32 v4, v0
	v_mov_b32_e32 v5, v0
	v_mov_b32_e32 v6, v0
	v_mov_b32_e32 v7, v0
	v_mov_b32_e32 v8, v0
	v_mov_b32_e32 v9, v0
	v_mov_b32_e32 v10, v0
	v_mov_b32_e32 v11, v0
	v_mov_b32_e32 v12, v0
	v_mov_b32_e32 v13, v0
	v_mov_b32_e32 v14, v0
	v_mov_b32_e32 v15, v0
	s_waitcnt vmcnt(0)
	v_mov_b32_e32 v112, v0
	v_mov_b32_e32 v113, v0
	v_mov_b32_e32 v114, v0
	v_mov_b32_e32 v115, v0
	v_mov_b32_e32 v116, v0
	v_mov_b32_e32 v117, v0
	v_mov_b32_e32 v118, v0
	v_mov_b32_e32 v119, v0
	v_mov_b32_e32 v144, v0
	v_mov_b32_e32 v145, v0
	v_mov_b32_e32 v146, v0
	v_mov_b32_e32 v147, v0
	v_mov_b32_e32 v148, v0
	v_mov_b32_e32 v149, v0
	v_mov_b32_e32 v150, v0
	v_mov_b32_e32 v151, v0
	s_nop 1
	v_mfma_f32_32x32x16_bf16 v[16:31], v[0:3], v[4:7], 0
	v_mfma_f32_32x32x16_bf16 v[32:47], v[0:3], v[4:7], 0
	v_mfma_f32_32x32x16_bf16 v[48:63], v[0:3], v[4:7], 0
	v_mfma_f32_32x32x16_bf16 v[64:79], v[0:3], v[4:7], 0
	v_mfma_f32_32x32x16_bf16 v[80:95], v[0:3], v[4:7], 0
	v_mfma_f32_32x32x16_bf16 v[96:111], v[0:3], v[4:7], 0

; template <class Epi>
; __device__ __forceinline__ void gemm_phase(LAS unsigned char* lds, const Gemm g, const StaticOrder& S, const Epi& E, int wave_s) {
;     ...
; #pragma unroll
;         for (int a = 0; a < 2; ++a)
; #pragma unroll
;             for (int b = 0; b < 2; ++b)
; #pragma unroll
;                 for (int m = 0; m < 4; ++m)
; #pragma unroll
;                     for (int n = 0; n < 2; ++n) acc[a][b][m][n] = (f32x4){0.f, 0.f, 0.f, 0.f};
.LBB0_1050:
	s_ashr_i32 s25, s24, 31
	s_lshl_b64 s[26:27], s[24:25], 19
	s_add_u32 s26, s0, s26
	s_addc_u32 s27, s1, s27
	s_and_b64 s[28:29], s[6:7], exec
	s_cselect_b32 s9, s27, s31
	s_cselect_b32 s25, s26, s30
	s_ashr_i32 s23, s22, 31
	s_lshl_b64 s[28:29], s[22:23], 19
	s_add_u32 s28, s3, s28
	s_addc_u32 s29, s4, s29
	s_and_b64 s[36:37], s[6:7], exec
	s_cselect_b32 s23, s29, s35
	s_cselect_b32 s52, s28, s34
	s_add_u32 s30, s30, 0x40080
	s_addc_u32 s31, s31, 0
	s_add_u32 s53, s34, 0x100
	v_mov_b32_e32 v0, 0
	s_addc_u32 s54, s35, 0
	s_mov_b32 s55, -2
	v_mov_b32_e32 v1, v0
	v_mov_b32_e32 v2, v0
	v_mov_b32_e32 v3, v0
	v_mov_b32_e32 v4, v0
	v_mov_b32_e32 v5, v0
	v_mov_b32_e32 v6, v0
	v_mov_b32_e32 v7, v0
	v_mov_b32_e32 v8, v0
	v_mov_b32_e32 v9, v0
	v_mov_b32_e32 v10, v0
	v_mov_b32_e32 v11, v0
	v_mov_b32_e32 v12, v0
	v_mov_b32_e32 v13, v0
	v_mov_b32_e32 v14, v0
	v_mov_b32_e32 v15, v0
	s_nop 1
	v_mfma_f32_32x32x16_bf16 v[16:31], v[0:3], v[4:7], 0
	v_mfma_f32_32x32x16_bf16 v[32:47], v[0:3], v[4:7], 0
	v_mfma_f32_32x32x16_bf16 v[48:63], v[0:3], v[4:7], 0
	v_mfma_f32_32x32x16_bf16 v[64:79], v[0:3], v[4:7], 0
	v_mfma_f32_32x32x16_bf16 v[80:95], v[0:3], v[4:7], 0
	v_mfma_f32_32x32x16_bf16 v[96:111], v[0:3], v[4:7], 0
	v_mfma_f32_32x32x16_bf16 v[112:127], v[0:3], v[4:7], 0

; template <class Epi>
; __device__ __forceinline__ void gemm_phase(LAS unsigned char* lds, const Gemm g, const StaticOrder& S, const Epi& E, int wave_s) {
;     ...
; #pragma unroll
;         for (int a = 0; a < 2; ++a)
; #pragma unroll
;             for (int b = 0; b < 2; ++b)
; #pragma unroll
;                 for (int m = 0; m < 4; ++m)
; #pragma unroll
;                     for (int n = 0; n < 2; ++n) acc[a][b][m][n] = (f32x4){0.f, 0.f, 0.f, 0.f};
.LBB0_1137:
	s_add_u32 s52, s30, 0x100
	v_mov_b32_e32 v0, 0
	s_addc_u32 s53, s31, 0
	s_mov_b32 s54, -2
	v_mov_b32_e32 v1, v0
	v_mov_b32_e32 v2, v0
	v_mov_b32_e32 v3, v0
	v_mov_b32_e32 v4, v0
	v_mov_b32_e32 v5, v0
	v_mov_b32_e32 v6, v0
	v_mov_b32_e32 v7, v0
	v_mov_b32_e32 v8, v0
	v_mov_b32_e32 v9, v0
	v_mov_b32_e32 v10, v0
	v_mov_b32_e32 v11, v0
	v_mov_b32_e32 v12, v0
	v_mov_b32_e32 v13, v0
	v_mov_b32_e32 v14, v0
	v_mov_b32_e32 v15, v0
	s_waitcnt vmcnt(0)
	v_mov_b32_e32 v112, v0
	v_mov_b32_e32 v113, v0
	v_mov_b32_e32 v114, v0
	v_mov_b32_e32 v115, v0
	v_mov_b32_e32 v116, v0
	v_mov_b32_e32 v117, v0
	v_mov_b32_e32 v118, v0
	v_mov_b32_e32 v119, v0
	v_mov_b32_e32 v144, v0
	v_mov_b32_e32 v145, v0
	v_mov_b32_e32 v146, v0
	v_mov_b32_e32 v147, v0
	v_mov_b32_e32 v148, v0
	v_mov_b32_e32 v149, v0
	v_mov_b32_e32 v150, v0
	v_mov_b32_e32 v151, v0
	s_nop 1
	v_mfma_f32_32x32x16_bf16 v[16:31], v[0:3], v[4:7], 0
	v_mfma_f32_32x32x16_bf16 v[32:47], v[0:3], v[4:7], 0
	v_mfma_f32_32x32x16_bf16 v[48:63], v[0:3], v[4:7], 0
	v_mfma_f32_32x32x16_bf16 v[64:79], v[0:3], v[4:7], 0
	v_mfma_f32_32x32x16_bf16 v[80:95], v[0:3], v[4:7], 0
	v_mfma_f32_32x32x16_bf16 v[96:111], v[0:3], v[4:7], 0

; template <class Epi>
; __device__ __forceinline__ void gemm_phase(LAS unsigned char* lds, const Gemm g, const StaticOrder& S, const Epi& E, int wave_s) {
;     ...
; #pragma unroll
;         for (int a = 0; a < 2; ++a)
; #pragma unroll
;             for (int b = 0; b < 2; ++b)
; #pragma unroll
;                 for (int m = 0; m < 4; ++m)
; #pragma unroll
;                     for (int n = 0; n < 2; ++n) acc[a][b][m][n] = (f32x4){0.f, 0.f, 0.f, 0.f};
.LBB0_1412:
	s_ashr_i32 s35, s34, 31
	s_lshl_b64 s[36:37], s[34:35], 19
	s_add_u32 s36, s0, s36
	s_addc_u32 s37, s1, s37
	s_and_b64 s[38:39], s[8:9], exec
	s_cselect_b32 s11, s37, s41
	s_cselect_b32 s13, s36, s40
	s_ashr_i32 s31, s30, 31
	s_lshl_b64 s[38:39], s[30:31], 19
	s_add_u32 s38, s3, s38
	s_addc_u32 s39, s4, s39
	s_and_b64 s[44:45], s[8:9], exec
	s_cselect_b32 s31, s39, s43
	s_cselect_b32 s35, s38, s42
	s_add_u32 s40, s40, 0x40080
	s_addc_u32 s41, s41, 0
	s_add_u32 s58, s42, 0x100
	v_mov_b32_e32 v0, 0
	s_addc_u32 s59, s43, 0
	s_mov_b32 s60, -2
	s_waitcnt lgkmcnt(0)
	v_mov_b32_e32 v1, v0
	v_mov_b32_e32 v2, v0
	v_mov_b32_e32 v3, v0
	v_mov_b32_e32 v4, v0
	v_mov_b32_e32 v5, v0
	v_mov_b32_e32 v6, v0
	v_mov_b32_e32 v7, v0
	v_mov_b32_e32 v8, v0
	v_mov_b32_e32 v9, v0
	v_mov_b32_e32 v10, v0
	v_mov_b32_e32 v11, v0
	v_mov_b32_e32 v12, v0
	v_mov_b32_e32 v13, v0
	v_mov_b32_e32 v14, v0
	v_mov_b32_e32 v15, v0
	s_nop 1
	v_mfma_f32_32x32x16_bf16 v[16:31], v[0:3], v[4:7], 0
	v_mfma_f32_32x32x16_bf16 v[32:47], v[0:3], v[4:7], 0
	v_mfma_f32_32x32x16_bf16 v[48:63], v[0:3], v[4:7], 0
	v_mfma_f32_32x32x16_bf16 v[64:79], v[0:3], v[4:7], 0
	v_mfma_f32_32x32x16_bf16 v[80:95], v[0:3], v[4:7], 0
	v_mfma_f32_32x32x16_bf16 v[96:111], v[0:3], v[4:7], 0
	v_mfma_f32_32x32x16_bf16 v[112:127], v[0:3], v[4:7], 0

; template <class Epi>
; __device__ __forceinline__ void gemm_phase(LAS unsigned char* lds, const Gemm g, const StaticOrder& S, const Epi& E, int wave_s) {
;     ...
; #pragma unroll
;         for (int a = 0; a < 2; ++a)
; #pragma unroll
;             for (int b = 0; b < 2; ++b)
; #pragma unroll
;                 for (int m = 0; m < 4; ++m)
; #pragma unroll
;                     for (int n = 0; n < 2; ++n) acc[a][b][m][n] = (f32x4){0.f, 0.f, 0.f, 0.f};
.LBB0_1523:
	s_ashr_i32 s29, s28, 31
	s_lshl_b64 s[30:31], s[28:29], 19
	s_add_u32 s30, s10, s30
	s_addc_u32 s31, s11, s31
	s_and_b64 s[34:35], s[6:7], exec
	s_cselect_b32 s29, s31, s37
	s_cselect_b32 s56, s30, s36
	s_ashr_i32 s27, s26, 31
	s_lshl_b64 s[34:35], s[26:27], 18
	s_add_u32 s34, s0, s34
	s_addc_u32 s35, s1, s35
	s_and_b64 s[40:41], s[6:7], exec
	s_cselect_b32 s27, s35, s39
	s_cselect_b32 s57, s34, s38
	s_add_u32 s36, s36, 0x40080
	s_addc_u32 s37, s37, 0
	s_add_u32 s58, s38, 0x100
	v_mov_b32_e32 v0, 0
	s_addc_u32 s59, s39, 0
	s_mov_b32 s60, -2
	v_mov_b32_e32 v1, v0
	v_mov_b32_e32 v2, v0
	v_mov_b32_e32 v3, v0
	v_mov_b32_e32 v4, v0
	v_mov_b32_e32 v5, v0
	v_mov_b32_e32 v6, v0
	v_mov_b32_e32 v7, v0
	v_mov_b32_e32 v8, v0
	v_mov_b32_e32 v9, v0
	v_mov_b32_e32 v10, v0
	v_mov_b32_e32 v11, v0
	v_mov_b32_e32 v12, v0
	v_mov_b32_e32 v13, v0
	v_mov_b32_e32 v14, v0
	v_mov_b32_e32 v15, v0
	s_nop 1
	v_mfma_f32_32x32x16_bf16 v[16:31], v[0:3], v[4:7], 0
	v_mfma_f32_32x32x16_bf16 v[32:47], v[0:3], v[4:7], 0
	v_mfma_f32_32x32x16_bf16 v[48:63], v[0:3], v[4:7], 0
	v_mfma_f32_32x32x16_bf16 v[64:79], v[0:3], v[4:7], 0
	v_mfma_f32_32x32x16_bf16 v[80:95], v[0:3], v[4:7], 0
	v_mfma_f32_32x32x16_bf16 v[96:111], v[0:3], v[4:7], 0
	v_mfma_f32_32x32x16_bf16 v[112:127], v[0:3], v[4:7], 0

; template <class Epi>
; __device__ __forceinline__ void gemm_phase(LAS unsigned char* lds, const Gemm g, const StaticOrder& S, const Epi& E, int wave_s) {
;     ...
; #pragma unroll
;         for (int a = 0; a < 2; ++a)
; #pragma unroll
;             for (int b = 0; b < 2; ++b)
; #pragma unroll
;                 for (int m = 0; m < 4; ++m)
; #pragma unroll
;                     for (int n = 0; n < 2; ++n) acc[a][b][m][n] = (f32x4){0.f, 0.f, 0.f, 0.f};
.LBB0_1569:
	s_ashr_i32 s37, s36, 31
	s_lshl_b64 s[38:39], s[36:37], 17
	s_add_u32 s38, s1, s38
	s_addc_u32 s39, s33, s39
	s_and_b64 s[40:41], s[6:7], exec
	s_cselect_b32 s37, s39, s11
	s_cselect_b32 s73, s38, s10
	s_ashr_i32 s35, s34, 31
	s_lshl_b64 s[40:41], s[34:35], 19
	s_add_u32 s40, s3, s40
	s_addc_u32 s41, s4, s41
	s_and_b64 s[44:45], s[6:7], exec
	v_mov_b32_e32 v0, 0
	s_cselect_b32 s35, s41, s9
	s_cselect_b32 s74, s40, s8
	s_mov_b32 s48, 0
	s_mov_b64 s[44:45], -1
	s_mov_b64 s[46:47], 0
	v_mov_b32_e32 v1, v0
	v_mov_b32_e32 v2, v0
	v_mov_b32_e32 v3, v0
	v_mov_b32_e32 v4, v0
	v_mov_b32_e32 v5, v0
	v_mov_b32_e32 v6, v0
	v_mov_b32_e32 v7, v0
	v_mov_b32_e32 v8, v0
	v_mov_b32_e32 v9, v0
	v_mov_b32_e32 v10, v0
	v_mov_b32_e32 v11, v0
	v_mov_b32_e32 v12, v0
	v_mov_b32_e32 v13, v0
	v_mov_b32_e32 v14, v0
	v_mov_b32_e32 v15, v0
	s_nop 1
	v_mfma_f32_32x32x16_bf16 v[16:31], v[0:3], v[4:7], 0
	v_mfma_f32_32x32x16_bf16 v[32:47], v[0:3], v[4:7], 0
	v_mfma_f32_32x32x16_bf16 v[48:63], v[0:3], v[4:7], 0
	v_mfma_f32_32x32x16_bf16 v[64:79], v[0:3], v[4:7], 0
	v_mfma_f32_32x32x16_bf16 v[80:95], v[0:3], v[4:7], 0
	v_mfma_f32_32x32x16_bf16 v[96:111], v[0:3], v[4:7], 0
	v_mfma_f32_32x32x16_bf16 v[112:127], v[0:3], v[4:7], 0

; template <class Epi>
; __device__ __forceinline__ void gemm_phase(LAS unsigned char* lds, const Gemm g, const StaticOrder& S, const Epi& E, int wave_s) {
;     ...
; #pragma unroll
;         for (int a = 0; a < 2; ++a)
; #pragma unroll
;             for (int b = 0; b < 2; ++b)
; #pragma unroll
;                 for (int m = 0; m < 4; ++m)
; #pragma unroll
;                     for (int n = 0; n < 2; ++n) acc[a][b][m][n] = (f32x4){0.f, 0.f, 0.f, 0.f};
.LBB0_2224:
	s_add_u32 s48, s24, 0x100
	v_mov_b32_e32 v0, 0
	s_addc_u32 s49, s25, 0
	s_mov_b32 s50, -2
	v_mov_b32_e32 v1, v0
	v_mov_b32_e32 v2, v0
	v_mov_b32_e32 v3, v0
	v_mov_b32_e32 v4, v0
	v_mov_b32_e32 v5, v0
	v_mov_b32_e32 v6, v0
	v_mov_b32_e32 v7, v0
	v_mov_b32_e32 v12, v0
	v_mov_b32_e32 v13, v0
	v_mov_b32_e32 v14, v0
	v_mov_b32_e32 v15, v0
	v_mov_b32_e32 v8, v0
	v_mov_b32_e32 v9, v0
	v_mov_b32_e32 v10, v0
	v_mov_b32_e32 v11, v0
	s_waitcnt vmcnt(0)
	s_nop 1
	v_mfma_f32_32x32x16_bf16 v[16:31], v[0:3], v[4:7], 0
	v_mfma_f32_32x32x16_bf16 v[32:47], v[0:3], v[4:7], 0
	v_mfma_f32_32x32x16_bf16 v[48:63], v[0:3], v[4:7], 0
	v_mfma_f32_32x32x16_bf16 v[64:79], v[0:3], v[4:7], 0
	v_mfma_f32_32x32x16_bf16 v[80:95], v[0:3], v[4:7], 0
	v_mfma_f32_32x32x16_bf16 v[96:111], v[0:3], v[4:7], 0
	v_mfma_f32_32x32x16_bf16 v[112:127], v[0:3], v[4:7], 0
